# row-norm part of phase 0 prefetches its next 4-row trip into a second register set (with the order swap)
# baseline (speedup 1.0000x reference)
.LBB0_444:
	v_mov_b32_e32 v0, v179
	v_readlane_b32 s0, v253, 28
	v_ashrrev_i32_e32 v1, 4, v0
	v_and_b32_e32 v1, -4, v1
	v_add_u32_e32 v80, s0, v1
	s_mov_b32 s0, 0x8000
	v_cmp_gt_i32_e32 vcc, s0, v80
	s_and_saveexec_b64 s[0:1], vcc
	s_mov_b32 s6, 0x3a800000
	s_mov_b32 s20, 0x3727c5ac
	s_cbranch_execz .Lp0_norm_done
	v_and_b32_e32 v16, 63, v0
	v_readlane_b32 s56, v252, 10
	v_lshlrev_b32_e32 v176, 4, v16
	v_readlane_b32 s58, v252, 12
	v_readlane_b32 s59, v252, 13
	s_nop 4
	global_load_dwordx4 v[0:3], v176, s[58:59]
	global_load_dwordx4 v[4:7], v176, s[58:59] offset:1024
	global_load_dwordx4 v[8:11], v176, s[58:59] offset:2048
	global_load_dwordx4 v[12:15], v176, s[58:59] offset:3072
	v_and_b32_e32 v17, 64, v225
	v_add_u32_e32 v17, 64, v17
	v_xor_b32_e32 v18, 32, v225
	v_cmp_lt_i32_e32 vcc, v18, v17
	s_load_dword s2, s[74:75], 0x0
	v_readlane_b32 s62, v252, 16
	v_cndmask_b32_e32 v18, v225, v18, vcc
	v_lshlrev_b32_e32 v102, 2, v18
	v_xor_b32_e32 v18, 16, v225
	v_cmp_lt_i32_e32 vcc, v18, v17
	v_readlane_b32 s63, v252, 17
	v_readlane_b32 s64, v252, 18
	v_cndmask_b32_e32 v18, v225, v18, vcc
	v_lshlrev_b32_e32 v103, 2, v18
	v_xor_b32_e32 v18, 8, v225
	v_cmp_lt_i32_e32 vcc, v18, v17
	v_readlane_b32 s65, v252, 19
	v_readlane_b32 s66, v252, 20
	v_cndmask_b32_e32 v18, v225, v18, vcc
	v_lshlrev_b32_e32 v104, 2, v18
	v_xor_b32_e32 v18, 4, v225
	v_cmp_lt_i32_e32 vcc, v18, v17
	v_readlane_b32 s67, v252, 21
	v_readlane_b32 s68, v252, 22
	v_cndmask_b32_e32 v18, v225, v18, vcc
	v_lshlrev_b32_e32 v105, 2, v18
	v_xor_b32_e32 v18, 2, v225
	v_cmp_lt_i32_e32 vcc, v18, v17
	v_readlane_b32 s69, v252, 23
	v_readlane_b32 s70, v252, 24
	v_cndmask_b32_e32 v18, v225, v18, vcc
	v_lshlrev_b32_e32 v106, 2, v18
	v_xor_b32_e32 v18, 1, v225
	v_readlane_b32 s71, v252, 25
	v_cmp_lt_i32_e32 vcc, v18, v17
	v_lshlrev_b32_e32 v16, 2, v16
	v_readlane_b32 s57, v252, 11
	v_readlane_b32 s68, v255, 14
	v_readlane_b32 s70, v255, 12
	v_readlane_b32 s62, v255, 10
	v_readlane_b32 s64, v255, 6
	v_cndmask_b32_e32 v17, v225, v18, vcc
	v_or_b32_e32 v18, 0x100, v16
	v_or_b32_e32 v20, 0x200, v16
	v_or_b32_e32 v22, 0x300, v16
	v_readlane_b32 s69, v255, 15
	v_readlane_b32 s71, v255, 13
	v_readlane_b32 s63, v255, 11
	v_readlane_b32 s65, v255, 7
	v_readlane_b32 s66, v255, 8
	v_readlane_b32 s67, v255, 9
	v_lshl_add_u64 v[82:83], s[56:57], 0, v[176:177]
	v_lshlrev_b32_e32 v107, 2, v17
	s_waitcnt lgkmcnt(0)
	s_lshl_b32 s2, s2, 5
	s_mov_b64 s[38:39], 0
	v_lshlrev_b32_e32 v176, 1, v16
	v_lshlrev_b32_e32 v84, 1, v18
	v_lshlrev_b32_e32 v86, 1, v20
	v_lshlrev_b32_e32 v88, 1, v22
	v_readlane_b32 s60, v252, 14
	v_readlane_b32 s61, v252, 15
	v_ashrrev_i32_e32 v81, 31, v80
	v_lshlrev_b64 v[16:17], 12, v[80:81]
	v_lshl_add_u64 v[16:17], v[82:83], 0, v[16:17]
	v_add_u32_e32 v94, 1, v80
	global_load_dwordx4 v[76:79], v[16:17], off nt
	global_load_dwordx4 v[72:75], v[16:17], off offset:1024 nt
	global_load_dwordx4 v[68:71], v[16:17], off offset:2048 nt
	global_load_dwordx4 v[64:67], v[16:17], off offset:3072 nt
	v_ashrrev_i32_e32 v95, 31, v94
	v_lshlrev_b64 v[16:17], 12, v[94:95]
	v_lshl_add_u64 v[16:17], v[82:83], 0, v[16:17]
	global_load_dwordx4 v[60:63], v[16:17], off nt
	global_load_dwordx4 v[56:59], v[16:17], off offset:1024 nt
	global_load_dwordx4 v[52:55], v[16:17], off offset:2048 nt
	global_load_dwordx4 v[48:51], v[16:17], off offset:3072 nt
	v_add_u32_e32 v92, 2, v80
	v_ashrrev_i32_e32 v93, 31, v92
	v_lshlrev_b64 v[16:17], 12, v[92:93]
	v_lshl_add_u64 v[16:17], v[82:83], 0, v[16:17]
	global_load_dwordx4 v[44:47], v[16:17], off nt
	global_load_dwordx4 v[40:43], v[16:17], off offset:1024 nt
	global_load_dwordx4 v[36:39], v[16:17], off offset:2048 nt
	global_load_dwordx4 v[32:35], v[16:17], off offset:3072 nt
	v_add_u32_e32 v90, 3, v80
	v_ashrrev_i32_e32 v91, 31, v90
	v_lshlrev_b64 v[16:17], 12, v[90:91]
	v_lshl_add_u64 v[16:17], v[82:83], 0, v[16:17]
	global_load_dwordx4 v[28:31], v[16:17], off nt
	global_load_dwordx4 v[24:27], v[16:17], off offset:1024 nt
	global_load_dwordx4 v[20:23], v[16:17], off offset:2048 nt
	s_nop 0
	global_load_dwordx4 v[16:19], v[16:17], off offset:3072 nt
.LBB0_446:
	v_add_u32_e32 v212, s2, v80
	v_cmp_ge_i32_e32 vcc, s13, v212
	v_mov_b32_e32 v214, v212
	v_ashrrev_i32_e32 v215, 31, v214
	v_lshlrev_b64 v[214:215], 12, v[214:215]
	v_lshl_add_u64 v[214:215], v[82:83], 0, v[214:215]
	v_cndmask_b32_e32 v214, v82, v214, vcc
	v_cndmask_b32_e32 v215, v83, v215, vcc
	global_load_dwordx4 v[124:127], v[214:215], off nt
	global_load_dwordx4 v[128:131], v[214:215], off offset:1024 nt
	global_load_dwordx4 v[132:135], v[214:215], off offset:2048 nt
	global_load_dwordx4 v[136:139], v[214:215], off offset:3072 nt
	v_add_u32_e32 v214, 1, v212
	v_ashrrev_i32_e32 v215, 31, v214
	v_lshlrev_b64 v[214:215], 12, v[214:215]
	v_lshl_add_u64 v[214:215], v[82:83], 0, v[214:215]
	v_cndmask_b32_e32 v214, v82, v214, vcc
	v_cndmask_b32_e32 v215, v83, v215, vcc
	global_load_dwordx4 v[140:143], v[214:215], off nt
	global_load_dwordx4 v[144:147], v[214:215], off offset:1024 nt
	global_load_dwordx4 v[148:151], v[214:215], off offset:2048 nt
	global_load_dwordx4 v[152:155], v[214:215], off offset:3072 nt
	v_add_u32_e32 v214, 2, v212
	v_ashrrev_i32_e32 v215, 31, v214
	v_lshlrev_b64 v[214:215], 12, v[214:215]
	v_lshl_add_u64 v[214:215], v[82:83], 0, v[214:215]
	v_cndmask_b32_e32 v214, v82, v214, vcc
	v_cndmask_b32_e32 v215, v83, v215, vcc
	global_load_dwordx4 v[156:159], v[214:215], off nt
	global_load_dwordx4 v[160:163], v[214:215], off offset:1024 nt
	global_load_dwordx4 v[164:167], v[214:215], off offset:2048 nt
	global_load_dwordx4 v[168:171], v[214:215], off offset:3072 nt
	v_add_u32_e32 v214, 3, v212
	v_ashrrev_i32_e32 v215, 31, v214
	v_lshlrev_b64 v[214:215], 12, v[214:215]
	v_lshl_add_u64 v[214:215], v[82:83], 0, v[214:215]
	v_cndmask_b32_e32 v214, v82, v214, vcc
	v_cndmask_b32_e32 v215, v83, v215, vcc
	global_load_dwordx4 v[172:175], v[214:215], off nt
	global_load_dwordx4 v[200:203], v[214:215], off offset:1024 nt
	global_load_dwordx4 v[204:207], v[214:215], off offset:2048 nt
	global_load_dwordx4 v[208:211], v[214:215], off offset:3072 nt
	v_ashrrev_i32_e32 v81, 31, v80
	v_add_u32_e32 v94, 1, v80
	v_ashrrev_i32_e32 v95, 31, v94
	v_add_u32_e32 v92, 2, v80
	v_ashrrev_i32_e32 v93, 31, v92
	v_add_u32_e32 v90, 3, v80
	v_ashrrev_i32_e32 v91, 31, v90
	v_mov_b32_e32 v85, v177
	s_waitcnt vmcnt(31)
	v_mov_b32_e32 v98, v77
	s_waitcnt vmcnt(30)
	v_mov_b32_e32 v99, v73
	s_waitcnt vmcnt(29)
	v_mov_b32_e32 v112, v69
	s_waitcnt vmcnt(28)
	v_mov_b32_e32 v113, v65
	v_mov_b32_e32 v110, v68
	v_mov_b32_e32 v111, v64
	v_pk_mul_f32 v[112:113], v[112:113], v[112:113]
	v_mov_b32_e32 v96, v76
	v_mov_b32_e32 v97, v72
	v_mov_b32_e32 v114, v70
	v_mov_b32_e32 v115, v66
	v_pk_mul_f32 v[98:99], v[98:99], v[98:99]
	v_pk_fma_f32 v[110:111], v[110:111], v[110:111], v[112:113]
	v_mov_b32_e32 v100, v78
	v_mov_b32_e32 v101, v74
	v_pk_fma_f32 v[96:97], v[96:97], v[96:97], v[98:99]
	v_pk_fma_f32 v[110:111], v[114:115], v[114:115], v[110:111]
	s_waitcnt vmcnt(25)
	v_mov_b32_e32 v114, v53
	s_waitcnt vmcnt(24)
	v_mov_b32_e32 v115, v49
	v_mov_b32_e32 v120, v61
	v_mov_b32_e32 v121, v57
	v_pk_fma_f32 v[96:97], v[100:101], v[100:101], v[96:97]
	v_mov_b32_e32 v100, v52
	v_mov_b32_e32 v101, v48
	v_pk_mul_f32 v[114:115], v[114:115], v[114:115]
	v_mov_b32_e32 v118, v60
	v_mov_b32_e32 v119, v56
	v_pk_mul_f32 v[120:121], v[120:121], v[120:121]
	v_pk_fma_f32 v[100:101], v[100:101], v[100:101], v[114:115]
	s_waitcnt vmcnt(23)
	v_mov_b32_e32 v114, v45
	s_waitcnt vmcnt(22)
	v_mov_b32_e32 v115, v41
	v_mov_b32_e32 v98, v62
	v_mov_b32_e32 v99, v58
	v_pk_fma_f32 v[118:119], v[118:119], v[118:119], v[120:121]
	v_mov_b32_e32 v120, v44
	v_mov_b32_e32 v121, v40
	v_pk_mul_f32 v[114:115], v[114:115], v[114:115]
	v_mov_b32_e32 v108, v79
	v_mov_b32_e32 v109, v75
	v_mov_b32_e32 v116, v71
	v_mov_b32_e32 v117, v67
	v_mov_b32_e32 v112, v63
	v_mov_b32_e32 v113, v59
	v_pk_fma_f32 v[114:115], v[120:121], v[120:121], v[114:115]
	v_mov_b32_e32 v120, v54
	v_mov_b32_e32 v121, v50
	v_pk_fma_f32 v[98:99], v[98:99], v[98:99], v[118:119]
	v_pk_fma_f32 v[108:109], v[108:109], v[108:109], v[96:97]
	v_mov_b32_e32 v96, v55
	v_mov_b32_e32 v97, v51
	v_pk_fma_f32 v[110:111], v[116:117], v[116:117], v[110:111]
	v_mov_b32_e32 v116, v46
	v_mov_b32_e32 v117, v42
	v_pk_fma_f32 v[100:101], v[120:121], v[120:121], v[100:101]
	v_pk_fma_f32 v[112:113], v[112:113], v[112:113], v[98:99]
	v_pk_fma_f32 v[114:115], v[116:117], v[116:117], v[114:115]
	v_pk_fma_f32 v[100:101], v[96:97], v[96:97], v[100:101]
	v_mov_b32_e32 v116, v112
	v_mov_b32_e32 v117, v108
	v_mov_b32_e32 v108, v113
	v_pk_add_f32 v[108:109], v[116:117], v[108:109]
	v_mov_b32_e32 v112, v100
	v_mov_b32_e32 v113, v110
	v_pk_add_f32 v[108:109], v[108:109], v[112:113]
	v_mov_b32_e32 v110, v101
	v_pk_add_f32 v[100:101], v[108:109], v[110:111]
	ds_bpermute_b32 v109, v102, v101
	ds_bpermute_b32 v108, v102, v100
	v_mov_b32_e32 v118, v47
	v_mov_b32_e32 v119, v43
	v_pk_fma_f32 v[96:97], v[118:119], v[118:119], v[114:115]
	s_waitcnt vmcnt(21)
	v_mov_b32_e32 v114, v37
	s_waitcnt lgkmcnt(0)
	v_pk_add_f32 v[100:101], v[100:101], v[108:109]
	ds_bpermute_b32 v109, v103, v101
	ds_bpermute_b32 v108, v103, v100
	s_waitcnt vmcnt(20)
	v_mov_b32_e32 v115, v33
	v_mov_b32_e32 v98, v36
	v_mov_b32_e32 v99, v32
	v_pk_mul_f32 v[114:115], v[114:115], v[114:115]
	s_waitcnt lgkmcnt(0)
	v_pk_add_f32 v[100:101], v[100:101], v[108:109]
	ds_bpermute_b32 v109, v104, v101
	ds_bpermute_b32 v108, v104, v100
	v_pk_fma_f32 v[98:99], v[98:99], v[98:99], v[114:115]
	v_mov_b32_e32 v114, v38
	v_mov_b32_e32 v115, v34
	v_pk_fma_f32 v[98:99], v[114:115], v[114:115], v[98:99]
	s_waitcnt lgkmcnt(0)
	v_pk_add_f32 v[100:101], v[100:101], v[108:109]
	ds_bpermute_b32 v109, v105, v101
	ds_bpermute_b32 v108, v105, v100
	v_mov_b32_e32 v114, v39
	v_mov_b32_e32 v115, v35
	s_waitcnt vmcnt(19)
	v_mov_b32_e32 v110, v29
	s_waitcnt vmcnt(18)
	v_mov_b32_e32 v111, v25
	s_waitcnt lgkmcnt(0)
	v_pk_add_f32 v[100:101], v[100:101], v[108:109]
	ds_bpermute_b32 v109, v106, v101
	ds_bpermute_b32 v108, v106, v100
	v_pk_fma_f32 v[98:99], v[114:115], v[114:115], v[98:99]
	v_mov_b32_e32 v114, v28
	v_mov_b32_e32 v115, v24
	v_pk_mul_f32 v[110:111], v[110:111], v[110:111]
	s_waitcnt lgkmcnt(0)
	v_pk_add_f32 v[100:101], v[100:101], v[108:109]
	ds_bpermute_b32 v109, v107, v101
	ds_bpermute_b32 v108, v107, v100
	v_pk_fma_f32 v[110:111], v[114:115], v[114:115], v[110:111]
	v_mov_b32_e32 v112, v30
	v_mov_b32_e32 v113, v26
	v_pk_fma_f32 v[110:111], v[112:113], v[112:113], v[110:111]
	v_mov_b32_e32 v112, v31
	v_mov_b32_e32 v113, v27
	s_waitcnt vmcnt(17)
	v_mov_b32_e32 v114, v21
	s_waitcnt vmcnt(16)
	v_mov_b32_e32 v115, v17
	v_pk_fma_f32 v[110:111], v[112:113], v[112:113], v[110:111]
	v_mov_b32_e32 v112, v20
	v_mov_b32_e32 v113, v16
	v_pk_mul_f32 v[114:115], v[114:115], v[114:115]
	s_waitcnt lgkmcnt(0)
	v_pk_add_f32 v[108:109], v[100:101], v[108:109]
	v_pk_fma_f32 v[112:113], v[112:113], v[112:113], v[114:115]
	v_mov_b32_e32 v114, v22
	v_mov_b32_e32 v115, v18
	v_mov_b64_e32 v[100:101], s[20:21]
	v_pk_fma_f32 v[112:113], v[114:115], v[114:115], v[112:113]
	v_mov_b32_e32 v114, v23
	v_mov_b32_e32 v115, v19
	v_pk_fma_f32 v[108:109], v[108:109], s[6:7], v[100:101] op_sel_hi:[1,0,0]
	v_pk_fma_f32 v[112:113], v[114:115], v[114:115], v[112:113]
	v_lshlrev_b64 v[114:115], 11, v[80:81]
	v_mul_f32_e32 v81, 0x4b800000, v109
	v_cmp_gt_f32_e32 vcc, s23, v109
	v_lshl_add_u64 v[114:115], s[50:51], 0, v[114:115]
	v_lshl_add_u64 v[116:117], v[114:115], 0, v[176:177]
	v_cndmask_b32_e32 v81, v109, v81, vcc
	v_rsq_f32_e32 v81, v81
	v_add_u32_e32 v80, s2, v80
	v_mul_f32_e32 v87, 0x45800000, v81
	v_cndmask_b32_e32 v118, v81, v87, vcc
	v_pk_mul_f32 v[76:77], v[76:77], v[118:119] op_sel_hi:[1,0]
	v_pk_mul_f32 v[78:79], v[78:79], v[118:119] op_sel_hi:[1,0]
	v_pk_mul_f32 v[76:77], v[0:1], v[76:77]
	v_pk_mul_f32 v[78:79], v[2:3], v[78:79]
	v_bfe_u32 v81, v76, 16, 1
	v_add3_u32 v81, v76, v81, s13
	v_bfe_u32 v76, v77, 16, 1
	v_add3_u32 v89, v77, v76, s13
	v_bfe_u32 v76, v78, 16, 1
	v_add3_u32 v109, v78, v76, s13
	v_bfe_u32 v76, v79, 16, 1
	v_add3_u32 v79, v79, v76, s13
	v_lshrrev_b32_e32 v78, 16, v81
	v_lshrrev_b32_e32 v81, 16, v109
	v_pk_mul_f32 v[72:73], v[72:73], v[118:119] op_sel_hi:[1,0]
	v_and_or_b32 v78, v89, s33, v78
	v_and_or_b32 v79, v79, s33, v81
	v_pk_mul_f32 v[72:73], v[4:5], v[72:73]
	global_store_dwordx2 v[116:117], v[78:79], off sc1
	v_bfe_u32 v78, v72, 16, 1
	v_pk_mul_f32 v[74:75], v[74:75], v[118:119] op_sel_hi:[1,0]
	v_add3_u32 v72, v72, v78, s13
	v_bfe_u32 v78, v73, 16, 1
	v_pk_mul_f32 v[74:75], v[6:7], v[74:75]
	v_lshrrev_b32_e32 v72, 16, v72
	v_add3_u32 v73, v73, v78, s13
	v_and_or_b32 v72, v73, s33, v72
	v_bfe_u32 v73, v74, 16, 1
	v_add3_u32 v73, v74, v73, s13
	v_bfe_u32 v74, v75, 16, 1
	v_lshrrev_b32_e32 v73, 16, v73
	v_add3_u32 v74, v75, v74, s13
	v_pk_mul_f32 v[68:69], v[68:69], v[118:119] op_sel_hi:[1,0]
	v_lshl_add_u64 v[76:77], v[114:115], 0, v[84:85]
	v_and_or_b32 v73, v74, s33, v73
	v_pk_mul_f32 v[68:69], v[8:9], v[68:69]
	global_store_dwordx2 v[76:77], v[72:73], off sc1
	v_bfe_u32 v72, v68, 16, 1
	v_pk_mul_f32 v[70:71], v[70:71], v[118:119] op_sel_hi:[1,0]
	v_add3_u32 v68, v68, v72, s13
	v_bfe_u32 v72, v69, 16, 1
	v_pk_mul_f32 v[70:71], v[10:11], v[70:71]
	v_lshrrev_b32_e32 v68, 16, v68
	v_add3_u32 v69, v69, v72, s13
	v_and_or_b32 v68, v69, s33, v68
	v_bfe_u32 v69, v70, 16, 1
	v_add3_u32 v69, v70, v69, s13
	v_bfe_u32 v70, v71, 16, 1
	v_mov_b32_e32 v87, v177
	v_lshrrev_b32_e32 v69, 16, v69
	v_add3_u32 v70, v71, v70, s13
	v_pk_mul_f32 v[64:65], v[64:65], v[118:119] op_sel_hi:[1,0]
	v_lshl_add_u64 v[120:121], v[114:115], 0, v[86:87]
	v_and_or_b32 v69, v70, s33, v69
	v_pk_mul_f32 v[64:65], v[12:13], v[64:65]
	global_store_dwordx2 v[120:121], v[68:69], off sc1
	v_bfe_u32 v68, v64, 16, 1
	v_add3_u32 v64, v64, v68, s13
	v_bfe_u32 v68, v65, 16, 1
	v_pk_mul_f32 v[66:67], v[66:67], v[118:119] op_sel_hi:[1,0]
	v_add3_u32 v65, v65, v68, s13
	v_mul_f32_e32 v68, 0x4b800000, v108
	v_cmp_gt_f32_e32 vcc, s23, v108
	v_pk_mul_f32 v[66:67], v[14:15], v[66:67]
	v_lshrrev_b32_e32 v64, 16, v64
	v_cndmask_b32_e32 v68, v108, v68, vcc
	v_and_or_b32 v64, v65, s33, v64
	v_bfe_u32 v65, v66, 16, 1
	v_rsq_f32_e32 v68, v68
	v_add3_u32 v65, v66, v65, s13
	v_bfe_u32 v66, v67, 16, 1
	v_mov_b32_e32 v89, v177
	v_lshrrev_b32_e32 v65, 16, v65
	v_add3_u32 v66, v67, v66, s13
	v_lshl_add_u64 v[114:115], v[114:115], 0, v[88:89]
	v_and_or_b32 v65, v66, s33, v65
	global_store_dwordx2 v[114:115], v[64:65], off sc1
	v_mul_f32_e32 v64, 0x45800000, v68
	v_cndmask_b32_e32 v64, v68, v64, vcc
	v_pk_mul_f32 v[60:61], v[60:61], v[64:65] op_sel_hi:[1,0]
	v_pk_mul_f32 v[62:63], v[62:63], v[64:65] op_sel_hi:[1,0]
	v_pk_mul_f32 v[60:61], v[0:1], v[60:61]
	v_pk_mul_f32 v[62:63], v[2:3], v[62:63]
	v_bfe_u32 v65, v60, 16, 1
	v_add3_u32 v60, v60, v65, s13
	v_bfe_u32 v65, v61, 16, 1
	v_lshrrev_b32_e32 v60, 16, v60
	v_add3_u32 v61, v61, v65, s13
	v_and_or_b32 v60, v61, s33, v60
	v_bfe_u32 v61, v62, 16, 1
	v_lshlrev_b64 v[66:67], 11, v[94:95]
	v_add3_u32 v61, v62, v61, s13
	v_bfe_u32 v62, v63, 16, 1
	v_lshl_add_u64 v[66:67], s[50:51], 0, v[66:67]
	v_lshrrev_b32_e32 v61, 16, v61
	v_add3_u32 v62, v63, v62, s13
	v_pk_mul_f32 v[56:57], v[56:57], v[64:65] op_sel_hi:[1,0]
	v_and_or_b32 v61, v62, s33, v61
	v_lshl_add_u64 v[62:63], v[66:67], 0, v[176:177]
	v_pk_mul_f32 v[56:57], v[4:5], v[56:57]
	global_store_dwordx2 v[62:63], v[60:61], off sc1
	v_bfe_u32 v60, v56, 16, 1
	v_pk_mul_f32 v[58:59], v[58:59], v[64:65] op_sel_hi:[1,0]
	v_add3_u32 v56, v56, v60, s13
	v_bfe_u32 v60, v57, 16, 1
	v_pk_mul_f32 v[58:59], v[6:7], v[58:59]
	v_lshrrev_b32_e32 v56, 16, v56
	v_add3_u32 v57, v57, v60, s13
	v_and_or_b32 v56, v57, s33, v56
	v_bfe_u32 v57, v58, 16, 1
	v_add3_u32 v57, v58, v57, s13
	v_bfe_u32 v58, v59, 16, 1
	v_lshrrev_b32_e32 v57, 16, v57
	v_add3_u32 v58, v59, v58, s13
	v_pk_mul_f32 v[52:53], v[52:53], v[64:65] op_sel_hi:[1,0]
	v_and_or_b32 v57, v58, s33, v57
	v_lshl_add_u64 v[58:59], v[66:67], 0, v[84:85]
	v_pk_mul_f32 v[52:53], v[8:9], v[52:53]
	global_store_dwordx2 v[58:59], v[56:57], off sc1
	v_bfe_u32 v56, v52, 16, 1
	v_pk_mul_f32 v[54:55], v[54:55], v[64:65] op_sel_hi:[1,0]
	v_add3_u32 v52, v52, v56, s13
	v_bfe_u32 v56, v53, 16, 1
	v_pk_mul_f32 v[54:55], v[10:11], v[54:55]
	v_lshrrev_b32_e32 v52, 16, v52
	v_add3_u32 v53, v53, v56, s13
	v_and_or_b32 v52, v53, s33, v52
	v_bfe_u32 v53, v54, 16, 1
	v_add3_u32 v53, v54, v53, s13
	v_bfe_u32 v54, v55, 16, 1
	v_add3_u32 v58, v55, v54, s13
	v_mov_b32_e32 v54, v110
	v_mov_b32_e32 v55, v96
	v_mov_b32_e32 v96, v111
	v_pk_add_f32 v[54:55], v[54:55], v[96:97]
	v_mov_b32_e32 v56, v112
	v_mov_b32_e32 v57, v98
	v_pk_add_f32 v[54:55], v[54:55], v[56:57]
	v_mov_b32_e32 v98, v113
	v_pk_add_f32 v[54:55], v[54:55], v[98:99]
	ds_bpermute_b32 v57, v102, v55
	ds_bpermute_b32 v56, v102, v54
	v_lshrrev_b32_e32 v53, 16, v53
	v_and_or_b32 v53, v58, s33, v53
	v_lshl_add_u64 v[58:59], v[66:67], 0, v[86:87]
	global_store_dwordx2 v[58:59], v[52:53], off sc1
	s_waitcnt lgkmcnt(0)
	v_pk_add_f32 v[52:53], v[54:55], v[56:57]
	ds_bpermute_b32 v55, v103, v53
	ds_bpermute_b32 v54, v103, v52
	v_pk_mul_f32 v[48:49], v[48:49], v[64:65] op_sel_hi:[1,0]
	v_pk_mul_f32 v[50:51], v[50:51], v[64:65] op_sel_hi:[1,0]
	v_pk_mul_f32 v[48:49], v[12:13], v[48:49]
	v_pk_mul_f32 v[50:51], v[14:15], v[50:51]
	s_waitcnt lgkmcnt(0)
	v_pk_add_f32 v[52:53], v[52:53], v[54:55]
	ds_bpermute_b32 v55, v104, v53
	ds_bpermute_b32 v54, v104, v52
	v_bfe_u32 v56, v48, 16, 1
	v_add3_u32 v48, v48, v56, s13
	v_lshrrev_b32_e32 v56, 16, v48
	v_bfe_u32 v48, v49, 16, 1
	v_add3_u32 v57, v49, v48, s13
	s_waitcnt lgkmcnt(0)
	v_pk_add_f32 v[48:49], v[52:53], v[54:55]
	ds_bpermute_b32 v53, v105, v49
	ds_bpermute_b32 v52, v105, v48
	v_bfe_u32 v55, v50, 16, 1
	v_add3_u32 v50, v50, v55, s13
	v_bfe_u32 v55, v51, 16, 1
	v_lshrrev_b32_e32 v50, 16, v50
	s_waitcnt lgkmcnt(0)
	v_pk_add_f32 v[48:49], v[48:49], v[52:53]
	ds_bpermute_b32 v53, v106, v49
	ds_bpermute_b32 v52, v106, v48
	v_add3_u32 v51, v51, v55, s13
	v_and_or_b32 v54, v57, s33, v56
	v_and_or_b32 v55, v51, s33, v50
	v_lshl_add_u64 v[50:51], v[66:67], 0, v[88:89]
	s_waitcnt lgkmcnt(0)
	v_pk_add_f32 v[48:49], v[48:49], v[52:53]
	ds_bpermute_b32 v53, v107, v49
	ds_bpermute_b32 v52, v107, v48
	global_store_dwordx2 v[50:51], v[54:55], off sc1
	v_lshlrev_b64 v[50:51], 11, v[92:93]
	v_lshl_add_u64 v[50:51], s[50:51], 0, v[50:51]
	v_lshl_add_u64 v[54:55], v[50:51], 0, v[176:177]
	s_waitcnt lgkmcnt(0)
	v_pk_add_f32 v[48:49], v[48:49], v[52:53]
	v_lshl_add_u64 v[56:57], v[50:51], 0, v[86:87]
	v_pk_fma_f32 v[48:49], v[48:49], s[6:7], v[100:101] op_sel_hi:[1,0,0]
	s_nop 0
	v_mul_f32_e32 v52, 0x4b800000, v49
	v_cmp_gt_f32_e32 vcc, s23, v49
	s_nop 1
	v_cndmask_b32_e32 v49, v49, v52, vcc
	v_rsq_f32_e32 v49, v49
	v_lshl_add_u64 v[52:53], v[50:51], 0, v[84:85]
	v_lshl_add_u64 v[50:51], v[50:51], 0, v[88:89]
	v_mul_f32_e32 v58, 0x45800000, v49
	v_cndmask_b32_e32 v58, v49, v58, vcc
	v_pk_mul_f32 v[44:45], v[44:45], v[58:59] op_sel_hi:[1,0]
	v_pk_mul_f32 v[46:47], v[46:47], v[58:59] op_sel_hi:[1,0]
	v_pk_mul_f32 v[44:45], v[0:1], v[44:45]
	v_pk_mul_f32 v[46:47], v[2:3], v[46:47]
	v_bfe_u32 v49, v44, 16, 1
	v_add3_u32 v44, v44, v49, s13
	v_bfe_u32 v49, v45, 16, 1
	v_lshrrev_b32_e32 v44, 16, v44
	v_add3_u32 v45, v45, v49, s13
	v_and_or_b32 v44, v45, s33, v44
	v_bfe_u32 v45, v46, 16, 1
	v_add3_u32 v45, v46, v45, s13
	v_bfe_u32 v46, v47, 16, 1
	v_lshrrev_b32_e32 v45, 16, v45
	v_add3_u32 v46, v47, v46, s13
	v_pk_mul_f32 v[40:41], v[40:41], v[58:59] op_sel_hi:[1,0]
	v_and_or_b32 v45, v46, s33, v45
	v_pk_mul_f32 v[40:41], v[4:5], v[40:41]
	global_store_dwordx2 v[54:55], v[44:45], off sc1
	v_bfe_u32 v44, v40, 16, 1
	v_pk_mul_f32 v[42:43], v[42:43], v[58:59] op_sel_hi:[1,0]
	v_add3_u32 v40, v40, v44, s13
	v_bfe_u32 v44, v41, 16, 1
	v_pk_mul_f32 v[42:43], v[6:7], v[42:43]
	v_lshrrev_b32_e32 v40, 16, v40
	v_add3_u32 v41, v41, v44, s13
	v_and_or_b32 v40, v41, s33, v40
	v_bfe_u32 v41, v42, 16, 1
	v_add3_u32 v41, v42, v41, s13
	v_bfe_u32 v42, v43, 16, 1
	v_lshrrev_b32_e32 v41, 16, v41
	v_add3_u32 v42, v43, v42, s13
	v_pk_mul_f32 v[36:37], v[36:37], v[58:59] op_sel_hi:[1,0]
	v_and_or_b32 v41, v42, s33, v41
	v_pk_mul_f32 v[36:37], v[8:9], v[36:37]
	global_store_dwordx2 v[52:53], v[40:41], off sc1
	v_bfe_u32 v40, v36, 16, 1
	v_pk_mul_f32 v[38:39], v[38:39], v[58:59] op_sel_hi:[1,0]
	v_add3_u32 v36, v36, v40, s13
	v_bfe_u32 v40, v37, 16, 1
	v_pk_mul_f32 v[38:39], v[10:11], v[38:39]
	v_lshrrev_b32_e32 v36, 16, v36
	v_add3_u32 v37, v37, v40, s13
	v_and_or_b32 v36, v37, s33, v36
	v_bfe_u32 v37, v38, 16, 1
	v_add3_u32 v37, v38, v37, s13
	v_bfe_u32 v38, v39, 16, 1
	v_lshrrev_b32_e32 v37, 16, v37
	v_add3_u32 v38, v39, v38, s13
	v_pk_mul_f32 v[32:33], v[32:33], v[58:59] op_sel_hi:[1,0]
	v_and_or_b32 v37, v38, s33, v37
	v_pk_mul_f32 v[32:33], v[12:13], v[32:33]
	global_store_dwordx2 v[56:57], v[36:37], off sc1
	v_bfe_u32 v36, v32, 16, 1
	v_add3_u32 v32, v32, v36, s13
	v_bfe_u32 v36, v33, 16, 1
	v_pk_mul_f32 v[34:35], v[34:35], v[58:59] op_sel_hi:[1,0]
	v_add3_u32 v33, v33, v36, s13
	v_mul_f32_e32 v36, 0x4b800000, v48
	v_cmp_gt_f32_e32 vcc, s23, v48
	v_pk_mul_f32 v[34:35], v[14:15], v[34:35]
	v_lshrrev_b32_e32 v32, 16, v32
	v_cndmask_b32_e32 v36, v48, v36, vcc
	v_and_or_b32 v32, v33, s33, v32
	v_bfe_u32 v33, v34, 16, 1
	v_rsq_f32_e32 v36, v36
	v_add3_u32 v33, v34, v33, s13
	v_bfe_u32 v34, v35, 16, 1
	v_lshrrev_b32_e32 v33, 16, v33
	v_add3_u32 v34, v35, v34, s13
	v_and_or_b32 v33, v34, s33, v33
	global_store_dwordx2 v[50:51], v[32:33], off sc1
	v_mul_f32_e32 v32, 0x45800000, v36
	v_cndmask_b32_e32 v32, v36, v32, vcc
	v_pk_mul_f32 v[28:29], v[28:29], v[32:33] op_sel_hi:[1,0]
	v_pk_mul_f32 v[30:31], v[30:31], v[32:33] op_sel_hi:[1,0]
	v_pk_mul_f32 v[28:29], v[0:1], v[28:29]
	v_pk_mul_f32 v[30:31], v[2:3], v[30:31]
	v_bfe_u32 v33, v28, 16, 1
	v_add3_u32 v28, v28, v33, s13
	v_bfe_u32 v33, v29, 16, 1
	v_lshrrev_b32_e32 v28, 16, v28
	v_add3_u32 v29, v29, v33, s13
	v_and_or_b32 v28, v29, s33, v28
	v_bfe_u32 v29, v30, 16, 1
	v_lshlrev_b64 v[34:35], 11, v[90:91]
	v_add3_u32 v29, v30, v29, s13
	v_bfe_u32 v30, v31, 16, 1
	v_lshl_add_u64 v[34:35], s[50:51], 0, v[34:35]
	v_lshrrev_b32_e32 v29, 16, v29
	v_add3_u32 v30, v31, v30, s13
	v_pk_mul_f32 v[24:25], v[24:25], v[32:33] op_sel_hi:[1,0]
	v_and_or_b32 v29, v30, s33, v29
	v_lshl_add_u64 v[30:31], v[34:35], 0, v[176:177]
	v_pk_mul_f32 v[24:25], v[4:5], v[24:25]
	global_store_dwordx2 v[30:31], v[28:29], off sc1
	v_bfe_u32 v28, v24, 16, 1
	v_pk_mul_f32 v[26:27], v[26:27], v[32:33] op_sel_hi:[1,0]
	v_add3_u32 v24, v24, v28, s13
	v_bfe_u32 v28, v25, 16, 1
	v_pk_mul_f32 v[26:27], v[6:7], v[26:27]
	v_lshrrev_b32_e32 v24, 16, v24
	v_add3_u32 v25, v25, v28, s13
	v_and_or_b32 v24, v25, s33, v24
	v_bfe_u32 v25, v26, 16, 1
	v_add3_u32 v25, v26, v25, s13
	v_bfe_u32 v26, v27, 16, 1
	v_lshrrev_b32_e32 v25, 16, v25
	v_add3_u32 v26, v27, v26, s13
	v_pk_mul_f32 v[20:21], v[20:21], v[32:33] op_sel_hi:[1,0]
	v_and_or_b32 v25, v26, s33, v25
	v_lshl_add_u64 v[26:27], v[34:35], 0, v[84:85]
	v_pk_mul_f32 v[20:21], v[8:9], v[20:21]
	global_store_dwordx2 v[26:27], v[24:25], off sc1
	v_bfe_u32 v24, v20, 16, 1
	v_pk_mul_f32 v[22:23], v[22:23], v[32:33] op_sel_hi:[1,0]
	v_add3_u32 v20, v20, v24, s13
	v_bfe_u32 v24, v21, 16, 1
	v_pk_mul_f32 v[22:23], v[10:11], v[22:23]
	v_lshrrev_b32_e32 v20, 16, v20
	v_add3_u32 v21, v21, v24, s13
	v_and_or_b32 v20, v21, s33, v20
	v_bfe_u32 v21, v22, 16, 1
	v_add3_u32 v21, v22, v21, s13
	v_bfe_u32 v22, v23, 16, 1
	v_lshrrev_b32_e32 v21, 16, v21
	v_add3_u32 v22, v23, v22, s13
	v_pk_mul_f32 v[16:17], v[16:17], v[32:33] op_sel_hi:[1,0]
	v_and_or_b32 v21, v22, s33, v21
	v_lshl_add_u64 v[22:23], v[34:35], 0, v[86:87]
	v_pk_mul_f32 v[16:17], v[12:13], v[16:17]
	global_store_dwordx2 v[22:23], v[20:21], off sc1
	v_bfe_u32 v20, v16, 16, 1
	v_pk_mul_f32 v[18:19], v[18:19], v[32:33] op_sel_hi:[1,0]
	v_add3_u32 v16, v16, v20, s13
	v_bfe_u32 v20, v17, 16, 1
	v_pk_mul_f32 v[18:19], v[14:15], v[18:19]
	v_lshrrev_b32_e32 v16, 16, v16
	v_add3_u32 v17, v17, v20, s13
	v_and_or_b32 v16, v17, s33, v16
	v_bfe_u32 v17, v18, 16, 1
	v_add3_u32 v17, v18, v17, s13
	v_bfe_u32 v18, v19, 16, 1
	v_lshrrev_b32_e32 v17, 16, v17
	v_add3_u32 v18, v19, v18, s13
	v_cmp_lt_i32_e32 vcc, s13, v80
	v_and_or_b32 v17, v18, s33, v17
	v_lshl_add_u64 v[18:19], v[34:35], 0, v[88:89]
	s_or_b64 s[38:39], vcc, s[38:39]
	global_store_dwordx2 v[18:19], v[16:17], off sc1
	s_nop 1
	s_waitcnt vmcnt(16)
	v_mov_b32_e32 v76, v124
	v_mov_b32_e32 v77, v125
	v_mov_b32_e32 v78, v126
	v_mov_b32_e32 v79, v127
	v_mov_b32_e32 v72, v128
	v_mov_b32_e32 v73, v129
	v_mov_b32_e32 v74, v130
	v_mov_b32_e32 v75, v131
	v_mov_b32_e32 v68, v132
	v_mov_b32_e32 v69, v133
	v_mov_b32_e32 v70, v134
	v_mov_b32_e32 v71, v135
	v_mov_b32_e32 v64, v136
	v_mov_b32_e32 v65, v137
	v_mov_b32_e32 v66, v138
	v_mov_b32_e32 v67, v139
	v_mov_b32_e32 v60, v140
	v_mov_b32_e32 v61, v141
	v_mov_b32_e32 v62, v142
	v_mov_b32_e32 v63, v143
	v_mov_b32_e32 v56, v144
	v_mov_b32_e32 v57, v145
	v_mov_b32_e32 v58, v146
	v_mov_b32_e32 v59, v147
	v_mov_b32_e32 v52, v148
	v_mov_b32_e32 v53, v149
	v_mov_b32_e32 v54, v150
	v_mov_b32_e32 v55, v151
	v_mov_b32_e32 v48, v152
	v_mov_b32_e32 v49, v153
	v_mov_b32_e32 v50, v154
	v_mov_b32_e32 v51, v155
	v_mov_b32_e32 v44, v156
	v_mov_b32_e32 v45, v157
	v_mov_b32_e32 v46, v158
	v_mov_b32_e32 v47, v159
	v_mov_b32_e32 v40, v160
	v_mov_b32_e32 v41, v161
	v_mov_b32_e32 v42, v162
	v_mov_b32_e32 v43, v163
	v_mov_b32_e32 v36, v164
	v_mov_b32_e32 v37, v165
	v_mov_b32_e32 v38, v166
	v_mov_b32_e32 v39, v167
	v_mov_b32_e32 v32, v168
	v_mov_b32_e32 v33, v169
	v_mov_b32_e32 v34, v170
	v_mov_b32_e32 v35, v171
	v_mov_b32_e32 v28, v172
	v_mov_b32_e32 v29, v173
	v_mov_b32_e32 v30, v174
	v_mov_b32_e32 v31, v175
	v_mov_b32_e32 v24, v200
	v_mov_b32_e32 v25, v201
	v_mov_b32_e32 v26, v202
	v_mov_b32_e32 v27, v203
	v_mov_b32_e32 v20, v204
	v_mov_b32_e32 v21, v205
	v_mov_b32_e32 v22, v206
	v_mov_b32_e32 v23, v207
	v_mov_b32_e32 v16, v208
	v_mov_b32_e32 v17, v209
	v_mov_b32_e32 v18, v210
	v_mov_b32_e32 v19, v211
	s_andn2_b64 exec, exec, s[38:39]
	s_cbranch_execnz .LBB0_446
	s_branch .Lp0_norm_done
